# prologue weight transpose rewritten for 64x64 tiles: 64 full-row 256B loads in flight per wave (2x MLP), progressive vmcnt, pipelined LDS reads, full-line WT stores
# baseline (speedup 1.0000x reference)
; #define LAS __attribute__((address_space(3)))
; __device__ __forceinline__ const float* inp(const Params& P, int i) { asm volatile("" : "+s"(i)); return P.in[i]; }
; __device__ __forceinline__ void p0_transpose_item(const float* W, int N, bf16_t* WT, int k0, int n0, int nsrc0, LAS float* scr, int lane) {
;     float t[32];
;     const float* wp = W + (size_t)(k0 + (lane >> 5)) * N + nsrc0 + (lane & 31);
; #pragma unroll
;     for (int i = 0; i < 32; ++i) t[i] = wp[(size_t)(2 * i) * N];
; __device__ __forceinline__ void phase_prologue(const Params& P, LAS unsigned char* lds) {
;     ...
;     for (int it = gw; it < IT_TOTAL; it += NGW) {
;         int r = it; const float* W; bf16_t* WT; int N, kind;
;         if (r < 2 * IT_AB_IN) { const int i = r / IT_AB_IN; r -= i * IT_AB_IN; N = N_AB; kind = 0; W = inp(P, I_AB_WIN) + (size_t)i * DM * N_AB; WT = (bf16_t*)(ws + WS_WAB_IN + i * SZ_WAB_IN); }
;         else if ((r -= 2 * IT_AB_IN) < 2 * IT_OUT) { const int i = r / IT_OUT; r -= i * IT_OUT; N = DM; kind = 2; W = inp(P, I_AB_WOUT) + (size_t)i * DM * DM; WT = (bf16_t*)(ws + WS_WAB_OUT + i * SZ_WOUT); }
;         else if ((r -= 2 * IT_OUT) < 2 * IT_SG_IN) { const int i = r / IT_SG_IN; r -= i * IT_SG_IN; N = N_SG; kind = 1; W = inp(P, I_SG_WIN) + (size_t)i * DM * N_SG; WT = (bf16_t*)(ws + WS_WSG_IN + i * SZ_WSG_IN); }
;         else { r -= 2 * IT_SG_IN; const int i = r / IT_OUT; r -= i * IT_OUT; N = DM; kind = 2; W = inp(P, I_SG_WOUT) + (size_t)i * DM * DM; WT = (bf16_t*)(ws + WS_WSG_OUT + i * SZ_WOUT); }
;         const int nblk = N / 32, kb = r / nblk, nb = r % nblk, n0 = nb * 32;
;         const int ns = kind == 0 ? src_col_ab_in(n0) : (kind == 1 ? src_col_sg_in(n0) : n0);
;         p0_transpose_item(W, N, WT, kb * 64, n0, ns, scr, lane);
.LBB0_758:
	s_andn2_b64 vcc, exec, s[12:13]
	s_cbranch_vccnz .LBB0_8
	v_mov_b32_e32 v24, v178
	s_load_dwordx4 s[24:27], s[0:1], 0x90
	v_readfirstlane_b32 s6, v24
	s_ashr_i32 s5, s6, 6
	v_and_b32_e32 v4, 63, v24
	s_add_i32 s4, s5, s36
	s_lshl_b32 s4, s4, 1
	s_waitcnt lgkmcnt(0)
	s_mov_b64 s[12:13], s[26:27]
	s_cmp_gt_i32 s4, 0x8fff
	v_and_b32_e32 v25, 31, v24
	v_lshlrev_b32_e32 v21, 3, v4
	s_cbranch_scc1 .LBB0_788
	s_mul_i32 s2, s5, 0x2200
	s_add_i32 s2, s2, 0
	s_add_u32 s7, s12, 0x8000000
	s_addc_u32 s8, s13, 0
	s_add_u32 s9, s12, 0x5000000
	s_addc_u32 s44, s13, 0
	v_lshrrev_b32_e32 v5, 5, v4
	v_lshrrev_b32_e32 v6, 3, v4
	v_and_b32_e32 v0, 56, v21
	s_add_u32 s45, s12, 0x4000000
	v_lshl_add_u32 v2, v25, 2, s2
	v_mul_u32_u24_e32 v3, 0x84, v5
	v_mul_u32_u24_e32 v7, 0x84, v0
	v_lshlrev_b32_e32 v8, 2, v6
	s_addc_u32 s46, s13, 0
	v_add3_u32 v7, s2, v7, v8
	v_or_b32_e32 v8, 8, v6
	v_or_b32_e32 v9, 16, v6
	v_or_b32_e32 v10, 24, v6
	v_add_u32_e32 v11, v2, v3
	v_lshlrev_b32_e32 v2, 1, v0
	s_branch .LBB0_762
.LBB0_761:
	s_lshl_b32 s24, s20, 6
	s_mul_i32 s25, s24, s2
	s_add_i32 s25, s25, s40
	s_lshl_b32 s25, s25, 2
	s_add_u32 s26, s22, s25
	s_addc_u32 s27, s23, 0
	s_lshl_b32 s30, s2, 2
	s_mul_i32 s33, s5, 0x4100
	v_and_b32_e32 v18, 63, v178
	v_lshlrev_b32_e32 v12, 2, v18
	v_add_u32_e32 v13, s33, v12
	v_and_b32_e32 v16, 7, v18
	v_lshrrev_b32_e32 v17, 3, v18
	v_mul_u32_u24_e32 v14, 0x820, v16
	v_lshl_add_u32 v14, v17, 2, v14
	v_add_u32_e32 v14, s33, v14
	v_add_u32_e32 v15, s3, v17
	v_lshlrev_b32_e32 v15, 12, v15
	v_lshl_add_u32 v15, v16, 4, v15
	global_load_dword v66, v12, s[26:27]
	s_add_u32 s26, s26, s30
	s_addc_u32 s27, s27, 0
	global_load_dword v67, v12, s[26:27]
	s_add_u32 s26, s26, s30
	s_addc_u32 s27, s27, 0
	global_load_dword v68, v12, s[26:27]
	s_add_u32 s26, s26, s30
	s_addc_u32 s27, s27, 0
	global_load_dword v69, v12, s[26:27]
	s_add_u32 s26, s26, s30
	s_addc_u32 s27, s27, 0
	global_load_dword v70, v12, s[26:27]
	s_add_u32 s26, s26, s30
	s_addc_u32 s27, s27, 0
	global_load_dword v71, v12, s[26:27]
	s_add_u32 s26, s26, s30
	s_addc_u32 s27, s27, 0
	global_load_dword v72, v12, s[26:27]
	s_add_u32 s26, s26, s30
	s_addc_u32 s27, s27, 0
	global_load_dword v73, v12, s[26:27]
	s_add_u32 s26, s26, s30
	s_addc_u32 s27, s27, 0
	global_load_dword v74, v12, s[26:27]
	s_add_u32 s26, s26, s30
	s_addc_u32 s27, s27, 0
	global_load_dword v75, v12, s[26:27]
	s_add_u32 s26, s26, s30
	s_addc_u32 s27, s27, 0
	global_load_dword v76, v12, s[26:27]
	s_add_u32 s26, s26, s30
	s_addc_u32 s27, s27, 0
	global_load_dword v77, v12, s[26:27]
	s_add_u32 s26, s26, s30
	s_addc_u32 s27, s27, 0
	global_load_dword v78, v12, s[26:27]
	s_add_u32 s26, s26, s30
	s_addc_u32 s27, s27, 0
	global_load_dword v79, v12, s[26:27]
	s_add_u32 s26, s26, s30
	s_addc_u32 s27, s27, 0
	global_load_dword v80, v12, s[26:27]
	s_add_u32 s26, s26, s30
	s_addc_u32 s27, s27, 0
	global_load_dword v81, v12, s[26:27]
	s_add_u32 s26, s26, s30
	s_addc_u32 s27, s27, 0
	global_load_dword v82, v12, s[26:27]
	s_add_u32 s26, s26, s30
	s_addc_u32 s27, s27, 0
	global_load_dword v83, v12, s[26:27]
	s_add_u32 s26, s26, s30
	s_addc_u32 s27, s27, 0
	global_load_dword v84, v12, s[26:27]
	s_add_u32 s26, s26, s30
	s_addc_u32 s27, s27, 0
	global_load_dword v85, v12, s[26:27]
	s_add_u32 s26, s26, s30
	s_addc_u32 s27, s27, 0
	global_load_dword v86, v12, s[26:27]
	s_add_u32 s26, s26, s30
	s_addc_u32 s27, s27, 0
	global_load_dword v87, v12, s[26:27]
	s_add_u32 s26, s26, s30
	s_addc_u32 s27, s27, 0
	global_load_dword v88, v12, s[26:27]
	s_add_u32 s26, s26, s30
	s_addc_u32 s27, s27, 0
	global_load_dword v89, v12, s[26:27]
	s_add_u32 s26, s26, s30
	s_addc_u32 s27, s27, 0
	global_load_dword v90, v12, s[26:27]
	s_add_u32 s26, s26, s30
	s_addc_u32 s27, s27, 0
	global_load_dword v91, v12, s[26:27]
	s_add_u32 s26, s26, s30
	s_addc_u32 s27, s27, 0
	global_load_dword v92, v12, s[26:27]
	s_add_u32 s26, s26, s30
	s_addc_u32 s27, s27, 0
	global_load_dword v93, v12, s[26:27]
	s_add_u32 s26, s26, s30
	s_addc_u32 s27, s27, 0
	global_load_dword v94, v12, s[26:27]
	s_add_u32 s26, s26, s30
	s_addc_u32 s27, s27, 0
	global_load_dword v95, v12, s[26:27]
	s_add_u32 s26, s26, s30
	s_addc_u32 s27, s27, 0
	global_load_dword v96, v12, s[26:27]
	s_add_u32 s26, s26, s30
	s_addc_u32 s27, s27, 0
	global_load_dword v97, v12, s[26:27]
	s_add_u32 s26, s26, s30
	s_addc_u32 s27, s27, 0
	global_load_dword v98, v12, s[26:27]
	s_add_u32 s26, s26, s30
	s_addc_u32 s27, s27, 0
	global_load_dword v99, v12, s[26:27]
	s_add_u32 s26, s26, s30
	s_addc_u32 s27, s27, 0
	global_load_dword v100, v12, s[26:27]
	s_add_u32 s26, s26, s30
	s_addc_u32 s27, s27, 0
	global_load_dword v101, v12, s[26:27]
	s_add_u32 s26, s26, s30
	s_addc_u32 s27, s27, 0
	global_load_dword v102, v12, s[26:27]
	s_add_u32 s26, s26, s30
	s_addc_u32 s27, s27, 0
	global_load_dword v103, v12, s[26:27]
	s_add_u32 s26, s26, s30
	s_addc_u32 s27, s27, 0
	global_load_dword v104, v12, s[26:27]
	s_add_u32 s26, s26, s30
	s_addc_u32 s27, s27, 0
	global_load_dword v105, v12, s[26:27]
	s_add_u32 s26, s26, s30
	s_addc_u32 s27, s27, 0
	global_load_dword v106, v12, s[26:27]
	s_add_u32 s26, s26, s30
	s_addc_u32 s27, s27, 0
	global_load_dword v107, v12, s[26:27]
	s_add_u32 s26, s26, s30
	s_addc_u32 s27, s27, 0
	global_load_dword v108, v12, s[26:27]
	s_add_u32 s26, s26, s30
	s_addc_u32 s27, s27, 0
	global_load_dword v109, v12, s[26:27]
	s_add_u32 s26, s26, s30
	s_addc_u32 s27, s27, 0
	global_load_dword v110, v12, s[26:27]
	s_add_u32 s26, s26, s30
	s_addc_u32 s27, s27, 0
	global_load_dword v111, v12, s[26:27]
	s_add_u32 s26, s26, s30
	s_addc_u32 s27, s27, 0
	global_load_dword v112, v12, s[26:27]
	s_add_u32 s26, s26, s30
; __device__ __forceinline__ void lds_wait() { asm volatile("s_waitcnt lgkmcnt(0)" ::: "memory"); }
; __device__ __forceinline__ void p0_transpose_item(const float* W, int N, bf16_t* WT, int k0, int n0, int nsrc0, LAS float* scr, int lane) {
;     ...
;     for (int i = 0; i < 32; ++i) t[i] = wp[(size_t)(2 * i) * N];
; #pragma unroll
;     for (int i = 0; i < 32; ++i) scr[(2 * i + (lane >> 5)) * 33 + (lane & 31)] = t[i];
;     lds_wait();
	s_addc_u32 s27, s27, 0
	global_load_dword v113, v12, s[26:27]
	s_add_u32 s26, s26, s30
	s_addc_u32 s27, s27, 0
	global_load_dword v114, v12, s[26:27]
	s_add_u32 s26, s26, s30
	s_addc_u32 s27, s27, 0
	global_load_dword v115, v12, s[26:27]
	s_add_u32 s26, s26, s30
	s_addc_u32 s27, s27, 0
	global_load_dword v116, v12, s[26:27]
	s_add_u32 s26, s26, s30
	s_addc_u32 s27, s27, 0
	global_load_dword v117, v12, s[26:27]
	s_add_u32 s26, s26, s30
	s_addc_u32 s27, s27, 0
	global_load_dword v118, v12, s[26:27]
	s_add_u32 s26, s26, s30
	s_addc_u32 s27, s27, 0
	global_load_dword v119, v12, s[26:27]
	s_add_u32 s26, s26, s30
	s_addc_u32 s27, s27, 0
	global_load_dword v120, v12, s[26:27]
	s_add_u32 s26, s26, s30
	s_addc_u32 s27, s27, 0
	global_load_dword v121, v12, s[26:27]
	s_add_u32 s26, s26, s30
	s_addc_u32 s27, s27, 0
	global_load_dword v122, v12, s[26:27]
	s_add_u32 s26, s26, s30
	s_addc_u32 s27, s27, 0
	global_load_dword v123, v12, s[26:27]
	s_add_u32 s26, s26, s30
	s_addc_u32 s27, s27, 0
	global_load_dword v124, v12, s[26:27]
	s_add_u32 s26, s26, s30
	s_addc_u32 s27, s27, 0
	global_load_dword v125, v12, s[26:27]
	s_add_u32 s26, s26, s30
	s_addc_u32 s27, s27, 0
	global_load_dword v126, v12, s[26:27]
	s_add_u32 s26, s26, s30
	s_addc_u32 s27, s27, 0
	global_load_dword v127, v12, s[26:27]
	s_add_u32 s26, s26, s30
	s_addc_u32 s27, s27, 0
	global_load_dword v128, v12, s[26:27]
	s_add_u32 s26, s26, s30
	s_addc_u32 s27, s27, 0
	global_load_dword v129, v12, s[26:27]
	s_lshl_b32 s25, s24, 1
	s_add_u32 s16, s16, s25
	s_addc_u32 s17, s17, 0
	s_add_i32 s4, s4, s21
	s_add_i32 s4, s4, s21
	s_cmp_gt_i32 s4, 0x8fff
	s_waitcnt vmcnt(48)
	ds_write_b32 v13, v66
	ds_write_b32 v13, v67 offset:260
	ds_write_b32 v13, v68 offset:520
	ds_write_b32 v13, v69 offset:780
	ds_write_b32 v13, v70 offset:1040
	ds_write_b32 v13, v71 offset:1300
	ds_write_b32 v13, v72 offset:1560
	ds_write_b32 v13, v73 offset:1820
	ds_write_b32 v13, v74 offset:2080
	ds_write_b32 v13, v75 offset:2340
	ds_write_b32 v13, v76 offset:2600
	ds_write_b32 v13, v77 offset:2860
	ds_write_b32 v13, v78 offset:3120
	ds_write_b32 v13, v79 offset:3380
	ds_write_b32 v13, v80 offset:3640
	ds_write_b32 v13, v81 offset:3900
	s_waitcnt vmcnt(32)
	ds_write_b32 v13, v82 offset:4160
	ds_write_b32 v13, v83 offset:4420
	ds_write_b32 v13, v84 offset:4680
	ds_write_b32 v13, v85 offset:4940
	ds_write_b32 v13, v86 offset:5200
	ds_write_b32 v13, v87 offset:5460
	ds_write_b32 v13, v88 offset:5720
	ds_write_b32 v13, v89 offset:5980
	ds_write_b32 v13, v90 offset:6240
	ds_write_b32 v13, v91 offset:6500
	ds_write_b32 v13, v92 offset:6760
	ds_write_b32 v13, v93 offset:7020
	ds_write_b32 v13, v94 offset:7280
	ds_write_b32 v13, v95 offset:7540
	ds_write_b32 v13, v96 offset:7800
	ds_write_b32 v13, v97 offset:8060
	s_waitcnt vmcnt(16)
	ds_write_b32 v13, v98 offset:8320
	ds_write_b32 v13, v99 offset:8580
	ds_write_b32 v13, v100 offset:8840
	ds_write_b32 v13, v101 offset:9100
	ds_write_b32 v13, v102 offset:9360
	ds_write_b32 v13, v103 offset:9620
	ds_write_b32 v13, v104 offset:9880
	ds_write_b32 v13, v105 offset:10140
	ds_write_b32 v13, v106 offset:10400
	ds_write_b32 v13, v107 offset:10660
	ds_write_b32 v13, v108 offset:10920
	ds_write_b32 v13, v109 offset:11180
	ds_write_b32 v13, v110 offset:11440
	ds_write_b32 v13, v111 offset:11700
	ds_write_b32 v13, v112 offset:11960
	ds_write_b32 v13, v113 offset:12220
	s_waitcnt vmcnt(0)
	ds_write_b32 v13, v114 offset:12480
	ds_write_b32 v13, v115 offset:12740
	ds_write_b32 v13, v116 offset:13000
	ds_write_b32 v13, v117 offset:13260
	ds_write_b32 v13, v118 offset:13520
	ds_write_b32 v13, v119 offset:13780
	ds_write_b32 v13, v120 offset:14040
	ds_write_b32 v13, v121 offset:14300
	ds_write_b32 v13, v122 offset:14560
	ds_write_b32 v13, v123 offset:14820
	ds_write_b32 v13, v124 offset:15080
	ds_write_b32 v13, v125 offset:15340
	ds_write_b32 v13, v126 offset:15600
	ds_write_b32 v13, v127 offset:15860
	ds_write_b32 v13, v128 offset:16120
	ds_write_b32 v13, v129 offset:16380
	s_waitcnt lgkmcnt(0)
; #define LAS __attribute__((address_space(3)))
; __device__ __forceinline__ unsigned pk2(float lo, float hi) { unsigned r; asm("v_cvt_pk_bf16_f32 %0, %1, %2" : "=v"(r) : "v"(lo), "v"(hi)); return r; }
; __device__ __forceinline__ void lds_wait() { asm volatile("s_waitcnt lgkmcnt(0)" ::: "memory"); }
; __device__ __forceinline__ void p0_transpose_item(const float* W, int N, bf16_t* WT, int k0, int n0, int nsrc0, LAS float* scr, int lane) {
;     ...
;     const int c = lane & 7;
; #pragma unroll
;     for (int j = 0; j < 4; ++j) { const int n = (lane >> 3) + 8 * j; const LAS float* s = scr + (8 * c) * 33 + n;
;         u32x4 o; o.x = pk2(s[0 * 33], s[1 * 33]); o.y = pk2(s[2 * 33], s[3 * 33]); o.z = pk2(s[4 * 33], s[5 * 33]); o.w = pk2(s[6 * 33], s[7 * 33]);
;         *(u32x4*)(WT + (size_t)(n0 + n) * DM + k0 + 8 * c) = o; }
;     lds_wait();
	ds_read_b32 v66, v14
	ds_read_b32 v67, v14 offset:260
	ds_read_b32 v68, v14 offset:520
	ds_read_b32 v69, v14 offset:780
	ds_read_b32 v70, v14 offset:1040
	ds_read_b32 v71, v14 offset:1300
	ds_read_b32 v72, v14 offset:1560
	ds_read_b32 v73, v14 offset:1820
	ds_read_b32 v74, v14 offset:32
	ds_read_b32 v75, v14 offset:292
	ds_read_b32 v76, v14 offset:552
	ds_read_b32 v77, v14 offset:812
	ds_read_b32 v78, v14 offset:1072
	ds_read_b32 v79, v14 offset:1332
	ds_read_b32 v80, v14 offset:1592
	ds_read_b32 v81, v14 offset:1852
	s_waitcnt lgkmcnt(8)
	v_cvt_pk_bf16_f32 v130, v66, v67
	v_cvt_pk_bf16_f32 v131, v68, v69
	v_cvt_pk_bf16_f32 v132, v70, v71
	v_cvt_pk_bf16_f32 v133, v72, v73
	global_store_dwordx4 v15, v[130:133], s[16:17]
	v_add_u32_e32 v15, 0x8000, v15
	ds_read_b32 v66, v14 offset:64
	ds_read_b32 v67, v14 offset:324
	ds_read_b32 v68, v14 offset:584
	ds_read_b32 v69, v14 offset:844
	ds_read_b32 v70, v14 offset:1104
	ds_read_b32 v71, v14 offset:1364
	ds_read_b32 v72, v14 offset:1624
	ds_read_b32 v73, v14 offset:1884
	s_waitcnt lgkmcnt(8)
	v_cvt_pk_bf16_f32 v134, v74, v75
	v_cvt_pk_bf16_f32 v135, v76, v77
	v_cvt_pk_bf16_f32 v136, v78, v79
	v_cvt_pk_bf16_f32 v137, v80, v81
	global_store_dwordx4 v15, v[134:137], s[16:17]
	v_add_u32_e32 v15, 0x8000, v15
	ds_read_b32 v74, v14 offset:96
	ds_read_b32 v75, v14 offset:356
	ds_read_b32 v76, v14 offset:616
	ds_read_b32 v77, v14 offset:876
	ds_read_b32 v78, v14 offset:1136
	ds_read_b32 v79, v14 offset:1396
	ds_read_b32 v80, v14 offset:1656
	ds_read_b32 v81, v14 offset:1916
	s_waitcnt lgkmcnt(8)
	v_cvt_pk_bf16_f32 v130, v66, v67
	v_cvt_pk_bf16_f32 v131, v68, v69
	v_cvt_pk_bf16_f32 v132, v70, v71
	v_cvt_pk_bf16_f32 v133, v72, v73
	global_store_dwordx4 v15, v[130:133], s[16:17]
	v_add_u32_e32 v15, 0x8000, v15
	ds_read_b32 v66, v14 offset:128
	ds_read_b32 v67, v14 offset:388
	ds_read_b32 v68, v14 offset:648
	ds_read_b32 v69, v14 offset:908
	ds_read_b32 v70, v14 offset:1168
	ds_read_b32 v71, v14 offset:1428
	ds_read_b32 v72, v14 offset:1688
	ds_read_b32 v73, v14 offset:1948
	s_waitcnt lgkmcnt(8)
	v_cvt_pk_bf16_f32 v134, v74, v75
	v_cvt_pk_bf16_f32 v135, v76, v77
	v_cvt_pk_bf16_f32 v136, v78, v79
	v_cvt_pk_bf16_f32 v137, v80, v81
	global_store_dwordx4 v15, v[134:137], s[16:17]
	v_add_u32_e32 v15, 0x8000, v15
	ds_read_b32 v74, v14 offset:160
	ds_read_b32 v75, v14 offset:420
	ds_read_b32 v76, v14 offset:680
	ds_read_b32 v77, v14 offset:940
	ds_read_b32 v78, v14 offset:1200
	ds_read_b32 v79, v14 offset:1460
	ds_read_b32 v80, v14 offset:1720
	ds_read_b32 v81, v14 offset:1980
	s_waitcnt lgkmcnt(8)
	v_cvt_pk_bf16_f32 v130, v66, v67
	v_cvt_pk_bf16_f32 v131, v68, v69
	v_cvt_pk_bf16_f32 v132, v70, v71
	v_cvt_pk_bf16_f32 v133, v72, v73
	global_store_dwordx4 v15, v[130:133], s[16:17]
	v_add_u32_e32 v15, 0x8000, v15
	ds_read_b32 v66, v14 offset:192
	ds_read_b32 v67, v14 offset:452
	ds_read_b32 v68, v14 offset:712
	ds_read_b32 v69, v14 offset:972
	ds_read_b32 v70, v14 offset:1232
	ds_read_b32 v71, v14 offset:1492
	ds_read_b32 v72, v14 offset:1752
	ds_read_b32 v73, v14 offset:2012
	s_waitcnt lgkmcnt(8)
	v_cvt_pk_bf16_f32 v134, v74, v75
	v_cvt_pk_bf16_f32 v135, v76, v77
	v_cvt_pk_bf16_f32 v136, v78, v79
	v_cvt_pk_bf16_f32 v137, v80, v81
	global_store_dwordx4 v15, v[134:137], s[16:17]
	v_add_u32_e32 v15, 0x8000, v15
	ds_read_b32 v74, v14 offset:224
	ds_read_b32 v75, v14 offset:484
	ds_read_b32 v76, v14 offset:744
	ds_read_b32 v77, v14 offset:1004
	ds_read_b32 v78, v14 offset:1264
	ds_read_b32 v79, v14 offset:1524
	ds_read_b32 v80, v14 offset:1784
	ds_read_b32 v81, v14 offset:2044
	s_waitcnt lgkmcnt(8)
	v_cvt_pk_bf16_f32 v130, v66, v67
	v_cvt_pk_bf16_f32 v131, v68, v69
	v_cvt_pk_bf16_f32 v132, v70, v71
	v_cvt_pk_bf16_f32 v133, v72, v73
	global_store_dwordx4 v15, v[130:133], s[16:17]
	v_add_u32_e32 v15, 0x8000, v15
	s_waitcnt lgkmcnt(0)
	v_cvt_pk_bf16_f32 v134, v74, v75
	v_cvt_pk_bf16_f32 v135, v76, v77
	v_cvt_pk_bf16_f32 v136, v78, v79
	v_cvt_pk_bf16_f32 v137, v80, v81
	global_store_dwordx4 v15, v[134:137], s[16:17]
	v_add_u32_e32 v15, 0x8000, v15
	s_cbranch_scc1 .LBB0_788

; #define LAS __attribute__((address_space(3)))
; __device__ __forceinline__ const float* inp(const Params& P, int i) { asm volatile("" : "+s"(i)); return P.in[i]; }
; __device__ __forceinline__ float silu_f(float x) { return x * frcp(1.f + fexp2(-1.4426950408889634f * x)); }
; __device__ __forceinline__ void phase_prologue(const Params& P, LAS unsigned char* lds) {
;     ...
;     float* mod = (float*)(ws + WS_MOD);
;     LAS unsigned char* red = lds + 71680;
;     for (int it = blockIdx.x; it < 4 * 8 * 24; it += gridDim.x) {
;         const int L = it / 192, r = it % 192, kq = r / 24, cgp = r % 24, col = cgp * 256 + 4 * lane, k0 = kq * 256 + wave * 32;
;         const float* W = (L & 1) ? inp(P, I_SG_WMOD) + (size_t)(L >> 1) * DM * 6144 : inp(P, I_AB_WMOD) + (size_t)(L >> 1) * DM * 6144;
;         const float* bm = (L & 1) ? inp(P, I_SG_BMOD) + (L >> 1) * 6144 : inp(P, I_AB_BMOD) + (L >> 1) * 6144;
;         float sc[4];
; #pragma unroll
;         for (int b = 0; b < 4; ++b) sc[b] = silu_f(inp(P, I_C)[b * DM + k0 + (lane & 31)]);
;         f32x4 a[4];
; #pragma unroll
;         for (int b = 0; b < 4; ++b) a[b] = (f32x4){0.f, 0.f, 0.f, 0.f};
;         const float* wp = W + (size_t)k0 * 6144 + col;
.LBB0_788:
	s_barrier
	v_readlane_b32 s2, v252, 7
	v_readlane_b32 s3, v252, 8
	s_andn2_b64 vcc, exec, s[2:3]
	s_cbranch_vccnz .LBB0_801
	s_lshl_b32 s4, s5, 5
	v_lshlrev_b32_e32 v5, 2, v24
	s_cmp_lt_u32 s6, 64
	v_and_b32_e32 v0, 12, v5
	v_readlane_b32 s6, v252, 31
	s_mov_b64 s[2:3], 0x9080000
	s_cselect_b64 s[16:17], -1, 0
	v_add_u32_e32 v6, s6, v0
	v_mov_b32_e32 v0, 2
	v_lshlrev_b32_sdwa v0, v0, v24 dst_sel:DWORD dst_unused:UNUSED_PAD src0_sel:DWORD src1_sel:BYTE_0
	v_lshl_add_u64 v[2:3], s[12:13], 0, v[0:1]
	v_add_u32_e32 v0, 0x200, v24
	v_lshl_add_u64 v[18:19], v[2:3], 0, s[2:3]
	v_ashrrev_i32_e32 v0, 8, v0
	s_lshl_b32 s2, s5, 12
	v_ashrrev_i32_e32 v20, 8, v24
	v_lshlrev_b32_e32 v26, 2, v4
	v_and_b32_e32 v2, 0x3f0, v5
	v_lshl_add_u32 v3, v0, 10, v6
	v_lshlrev_b32_e32 v27, 4, v4
	s_add_i32 s8, s2, 0
	v_lshl_add_u32 v4, v20, 10, v6
	s_add_i32 s5, s6, s2
	s_add_i32 s6, s8, 0x11c00
	s_add_i32 s7, s8, 0x12000
	s_add_i32 s8, s8, 0x12400
	v_add_u32_e32 v28, v4, v2
	v_add_u32_e32 v29, v3, v2
	s_mov_b32 s9, s77
	s_branch .LBB0_791
